# v10 + no store drain before the LDS work-counter atomic + waves 4-7 run the weight transposes first while waves 0-3 start attention
# baseline (speedup 1.0000x reference)
; #define LAS __attribute__((address_space(3)))
; #define KP() ({ KArgs _p = kp; asm volatile("" : "+s"(_p)); _p; })
; __global__ void __launch_bounds__(512, 2) fwd_kernel(Args a_byval) {
;     ...
;         const float* sinks = KP()->in[14];
;         __syncthreads();
;         volatile LAS unsigned* wctr = (volatile LAS unsigned*)(lds + RING_BYTES + 8192 + 64);
;         if (tid == 0) *wctr = 0u;
;         __syncthreads();
;         for (;;) {
;             unsigned k = 0; if (lane == 0) k = __hip_atomic_fetch_add((LAS unsigned*)(lds + RING_BYTES + 8192 + 64), 1u, __ATOMIC_RELAXED, __HIP_MEMORY_SCOPE_WORKGROUP);
;             k = __builtin_amdgcn_readfirstlane(k);
;             if (k >= 19u * NREP(2)) {
;                 const int it = bx + 256 * (int)(k - 19u * NREP(2));
;                 if (it >= WI_ALL) break;
;                 weight_item(KP(), it, lane); continue; }
;             if (k >= 19u) k -= 19u;
.Lbt_skip:
	v_readlane_b32 s0, v253, 1
	v_readlane_b32 s1, v253, 2
	s_load_dwordx2 s[0:1], s[0:1], 0x70
	s_mov_b32 s13, 0
	v_cmp_eq_u32_e32 vcc, 0, v226
	s_waitcnt lgkmcnt(0)
	s_barrier
	s_and_saveexec_b64 s[4:5], vcc
	s_add_i32 s6, 0, 0x22040
	v_mov_b32_e32 v0, 0
	v_mov_b32_e32 v1, s6
	ds_write_b32 v1, v0
	s_or_b64 exec, exec, s[4:5]
	s_lshl_b32 s4, s60, 14
	s_add_i32 s31, s4, 0
	s_bfe_u32 s4, s2, 0x10002
	s_add_i32 s30, s2, 0xfffff600
	s_and_b32 s6, s2, 7
	s_mul_i32 s4, s4, 0x2c0000
	v_mov_b32_e32 v161, 0
	s_add_u32 s4, s36, s4
	v_lshrrev_b32_e32 v8, 5, v190
	v_lshlrev_b32_e32 v158, 4, v190
	v_mov_b32_e32 v159, v161
	s_addc_u32 s5, s37, 0
	v_and_b32_e32 v182, 31, v226
	v_lshl_add_u64 v[0:1], s[4:5], 0, v[158:159]
	s_mov_b64 s[4:5], 0x8400000
	v_lshlrev_b32_e32 v2, 4, v8
	v_mov_b32_e32 v3, v161
	v_lshl_add_u64 v[162:163], v[0:1], 0, s[4:5]
	s_mov_b64 s[4:5], 0x8a00000
	v_lshlrev_b32_e32 v4, 7, v182
	v_mov_b32_e32 v5, v161
	v_lshl_add_u64 v[6:7], s[36:37], 0, v[2:3]
	v_lshl_add_u64 v[164:165], v[0:1], 0, s[4:5]
	v_lshl_add_u64 v[4:5], v[6:7], 0, v[4:5]
	s_mov_b64 s[4:5], 0xc600000
	v_lshl_add_u64 v[166:167], v[4:5], 0, s[4:5]
	s_lshl_b32 s4, s6, 2
	s_add_u32 s14, s0, s4
	s_addc_u32 s15, s1, 0
	s_mul_i32 s0, s6, 0x440000
	s_add_u32 s0, s36, s0
	s_addc_u32 s1, s37, 0
	v_lshl_add_u64 v[4:5], s[0:1], 0, v[158:159]
	s_mov_b64 s[0:1], 0xd800000
	v_lshl_add_u64 v[168:169], v[4:5], 0, s[0:1]
	s_mov_b64 s[0:1], 0x6200000
	v_lshl_add_u64 v[170:171], v[4:5], 0, s[0:1]
	s_mov_b64 s[0:1], 0xb400000
	v_lshl_add_u64 v[172:173], v[6:7], 0, s[0:1]
	s_lshl_b32 s0, s6, 10
	s_add_i32 s4, s0, 0
	s_add_i32 s34, s4, 0x22100
	s_lshl_b32 s0, s6, 7
	s_add_u32 s0, s36, s0
	v_lshlrev_b32_e32 v160, 3, v8
	v_mov_b32_e32 v1, 0xfffffe00
	s_addc_u32 s1, s37, 0
	v_lshlrev_b32_e32 v0, 6, v182
	v_cmp_gt_u32_e32 vcc, 32, v190
	v_lshl_or_b32 v159, v8, 2, v1
	v_lshl_add_u64 v[4:5], s[0:1], 0, v[160:161]
	s_mov_b64 s[0:1], 0x3e00000
	v_add_u32_e32 v1, s4, v2
	v_mbcnt_lo_u32_b32 v185, -1, 0
	v_cmp_eq_u32_e64 s[8:9], 0, v190
	s_mul_i32 s33, s6, 0x4800
	v_cndmask_b32_e64 v183, 0, 1.0, vcc
	s_add_i32 s35, s2, 0xffffed00
	v_lshl_add_u64 v[174:175], v[4:5], 0, s[0:1]
	v_add_u32_e32 v184, 0x21c7c, v1
	s_add_i32 s42, 0, 0x22040
	s_mov_b64 s[16:17], 0x400
	s_add_i32 s43, s31, 0x400
	s_mov_b64 s[18:19], 0x800
	s_add_i32 s44, s31, 0x800
	s_mov_b64 s[20:21], 0xc00
	s_add_i32 s45, s31, 0xc00
	s_add_i32 s46, s31, 0x1000
	s_add_i32 s47, s31, 0x1400
	s_add_i32 s48, s31, 0x1800
	s_add_i32 s49, s31, 0x1c00
	s_add_i32 s50, s31, 0x2000
	s_add_i32 s51, s31, 0x2400
	s_add_i32 s52, s31, 0x2800
	s_add_i32 s53, s31, 0x2c00
	s_add_i32 s54, s31, 0x3000
	s_add_i32 s55, s31, 0x3400
	s_add_i32 s56, s31, 0x3800
	s_add_i32 s57, s31, 0x3c00
	s_mov_b32 s58, 0x3fb8aa3b
	v_mov_b32_e32 v177, 0x41000000
	v_lshlrev_b32_e32 v160, 1, v0
	s_mov_b32 s59, 0x10000
	s_mov_b32 s60, 0x1b000
	s_mov_b32 s61, 0x26000
	s_mov_b32 s62, 0x31000
	s_mov_b32 s63, 0x3c000
	s_mov_b32 s64, 0x47000
	s_mov_b32 s65, 0x52000
	s_mov_b32 s66, 0x5d000
	s_mov_b32 s67, 0x68000
	s_mov_b32 s68, 0x73000
	s_mov_b32 s69, 0x7e000
	s_mov_b32 s70, 0x89000
	s_mov_b32 s71, 0x94000
	s_mov_b32 s72, 0x9f000
	s_mov_b32 s73, 0xaa000
	s_mov_b32 s74, 0xb5000
	s_mov_b32 s75, 0xc0000
	s_mov_b32 s76, 0xcb000
	s_mov_b32 s77, 0xd6000
	s_mov_b32 s78, 0xe1000
	s_mov_b32 s79, 0xec000
	s_mov_b32 s80, 0xf7000
	s_mov_b32 s81, 0x102000
	s_mov_b32 s82, 0x10d000
	s_mov_b32 s83, 0x118000
	s_mov_b32 s84, 0x123000
	s_mov_b32 s85, 0x12e000
	s_mov_b32 s86, 0x139000
	s_mov_b32 s87, 0x144000
	s_mov_b32 s88, 0x14f000
	s_mov_b32 s89, 0x15a000
	s_mov_b64 s[22:23], 0x800000
	s_mov_b64 s[24:25], 0x600000
	s_mov_b32 s90, 0x600000
	v_mbcnt_hi_u32_b32 v186, -1, v185
	v_mov_b32_e32 v187, 0xf149f2ca
	s_waitcnt lgkmcnt(0)
	s_barrier
	v_readfirstlane_b32 s98, v226
	s_nop 3
	s_lshr_b32 s98, s98, 6
	s_add_i32 s98, s98, -4
	s_cmp_lt_i32 s98, 0
	s_cselect_b32 s98, -1, s98
	s_branch .LBB0_605

; #define LAS __attribute__((address_space(3)))
; #define KP() ({ KArgs _p = kp; asm volatile("" : "+s"(_p)); _p; })
; __global__ void __launch_bounds__(512, 2) fwd_kernel(Args a_byval) {
;     ...
;         for (;;) {
;             unsigned k = 0; if (lane == 0) k = __hip_atomic_fetch_add((LAS unsigned*)(lds + RING_BYTES + 8192 + 64), 1u, __ATOMIC_RELAXED, __HIP_MEMORY_SCOPE_WORKGROUP);
;             k = __builtin_amdgcn_readfirstlane(k);
;             if (k >= 19u * NREP(2)) {
;                 const int it = bx + 256 * (int)(k - 19u * NREP(2));
;                 if (it >= WI_ALL) break;
;                 weight_item(KP(), it, lane); continue; }
.LBB0_604:
	s_and_b64 vcc, exec, s[0:1]
	s_cbranch_vccnz .LBB0_711
	s_branch .LBB0_605
.Lwq_wdone:
	s_mov_b32 s98, -1
.LBB0_605:
	s_cmp_lt_i32 s98, 0
	s_cbranch_scc1 .Lwq_attn
	s_add_i32 s12, s98, 19
	s_add_i32 s98, s98, 4
	s_mov_b64 s[0:1], -1
	s_branch .LBB0_699
.Lwq_attn:
	v_mov_b32_e32 v0, 0
	s_and_saveexec_b64 s[0:1], s[8:9]
	s_cbranch_execz .LBB0_609
	s_mov_b64 s[6:7], exec
	v_mbcnt_lo_u32_b32 v0, s6, 0
	v_mbcnt_hi_u32_b32 v0, s7, v0
	v_cmp_eq_u32_e32 vcc, 0, v0
	s_and_saveexec_b64 s[4:5], vcc
	s_cbranch_execz .LBB0_608
	s_bcnt1_i32_b64 s6, s[6:7]
	v_mov_b32_e32 v1, s42
	v_mov_b32_e32 v2, s6
	ds_add_rtn_u32 v1, v1, v2
